# bh2 variant: role alternation with 4-unit blocks (75% reordered)
# speedup vs baseline: 1.0035x; 1.0035x over previous
; #define SUB(k, bit) (!(kargs()->li == 1 && (k) == lo) || ((kargs()->submask >> (bit)) & 1u))
; __global__ void __launch_bounds__(NWAVES * 64, 2) fwd(Args args_unused) {
;     ...
;         if (IN(pb + 3)) {
;             PH_PTRS PH_LAYER
;             if (SUB(pb + 3, 0)) {
;                 const int nitems = (M / 16) * 5;
.LBB0_1364:
	v_readlane_b32 s99, v254, 3
	s_nop 3
	s_lshr_b32 s99, s99, 2
	s_and_b32 s99, s99, 3
	s_mov_b32 s98, 2
	s_cmp_eq_u32 s99, 1
	s_cselect_b32 s98, 0, s98
	s_cmp_eq_u32 s99, 2
	s_cselect_b32 s98, 0, s98
	s_cmp_eq_u32 s99, 3
	s_cselect_b32 s98, 0, s98
